# attention pass-2 loop: removed 16 redundant s_nop wait states before bf16 packs (none adjacent to its transcendental producer)
# speedup vs baseline: 1.0035x; 1.0035x over previous
.LBB0_131:
	global_load_dwordx4 v[88:91], v[108:109], off
	global_load_dwordx4 v[92:95], v[108:109], off offset:-16
	global_load_dwordx4 v[96:99], v[106:107], off
	global_load_dwordx4 v[100:103], v[106:107], off offset:-16
	s_add_i32 s5, s4, 1
	s_bitcmp1_b32 s4, 0
	s_cselect_b32 s4, s91, 0
	v_add_u32_e32 v132, s4, v118
	ds_read_b128 v[124:127], v132
	ds_read_b128 v[128:131], v132 offset:64
	ds_read_b128 v[150:153], v132 offset:128
	ds_read_b128 v[154:157], v132 offset:192
	ds_read_b128 v[158:161], v132 offset:4352
	ds_read_b128 v[162:165], v132 offset:4416
	ds_read_b128 v[166:169], v132 offset:4480
	ds_read_b128 v[170:173], v132 offset:4544
	ds_read_b128 v[174:177], v132 offset:8704
	ds_read_b128 v[178:181], v132 offset:8768
	ds_read_b128 v[182:185], v132 offset:8832
	ds_read_b128 v[186:189], v132 offset:8896
	ds_read_b128 v[216:219], v132 offset:13056
	ds_read_b128 v[220:223], v132 offset:13120
	ds_read_b128 v[224:227], v132 offset:13184
	ds_read_b128 v[228:231], v132 offset:13248
	s_cselect_b32 s4, s57, s70
	s_waitcnt lgkmcnt(14)
	v_mfma_f32_16x16x32_bf16 v[124:127], v[124:127], v[12:15], v[16:19]
	v_mfma_f32_16x16x32_bf16 v[124:127], v[128:131], v[0:3], v[124:127]
	s_waitcnt lgkmcnt(13)
	v_mfma_f32_16x16x32_bf16 v[128:131], v[150:153], v[4:7], v[20:23]
	s_waitcnt lgkmcnt(12)
	v_mfma_f32_16x16x32_bf16 v[128:131], v[154:157], v[8:11], v[128:131]
	s_waitcnt lgkmcnt(11)
	v_mfma_f32_16x16x32_bf16 v[150:153], v[158:161], v[12:15], v[16:19]
	s_waitcnt lgkmcnt(9)
	v_mfma_f32_16x16x32_bf16 v[154:157], v[166:169], v[4:7], v[20:23]
	v_mfma_f32_16x16x32_bf16 v[150:153], v[162:165], v[0:3], v[150:153]
	s_waitcnt lgkmcnt(8)
	v_mfma_f32_16x16x32_bf16 v[154:157], v[170:173], v[8:11], v[154:157]
	s_waitcnt lgkmcnt(7)
	v_mfma_f32_16x16x32_bf16 v[158:161], v[174:177], v[12:15], v[16:19]
	s_waitcnt lgkmcnt(5)
	v_mfma_f32_16x16x32_bf16 v[162:165], v[182:185], v[4:7], v[20:23]
	s_waitcnt lgkmcnt(3)
	v_mfma_f32_16x16x32_bf16 v[166:169], v[216:219], v[12:15], v[16:19]
	s_waitcnt lgkmcnt(1)
	v_mfma_f32_16x16x32_bf16 v[170:173], v[224:227], v[4:7], v[20:23]
	v_mfma_f32_16x16x32_bf16 v[158:161], v[178:181], v[0:3], v[158:161]
	v_mfma_f32_16x16x32_bf16 v[162:165], v[186:189], v[8:11], v[162:165]
	v_mfma_f32_16x16x32_bf16 v[166:169], v[220:223], v[0:3], v[166:169]
	s_waitcnt lgkmcnt(0)
	v_mfma_f32_16x16x32_bf16 v[170:173], v[228:231], v[8:11], v[170:173]
	v_add_u32_e32 v132, s4, v120
	v_add_u32_e32 v190, v132, v121
	ds_read_b128 v[174:177], v190
	ds_read_b128 v[178:181], v190 offset:2048
	ds_read_b128 v[182:185], v190 offset:4096
	ds_read_b128 v[186:189], v190 offset:6144
	ds_read_b128 v[216:219], v190 offset:8192
	ds_read_b128 v[220:223], v190 offset:10240
	ds_read_b128 v[224:227], v190 offset:12288
	ds_read_b128 v[228:231], v190 offset:14336
	v_exp_f32_e32 v191, v124
	v_exp_f32_e32 v190, v128
	v_exp_f32_e32 v241, v125
	v_exp_f32_e32 v240, v129
	v_exp_f32_e32 v243, v126
	v_exp_f32_e32 v242, v130
	v_exp_f32_e32 v245, v127
	v_exp_f32_e32 v244, v131
	v_exp_f32_e32 v247, v150
	v_exp_f32_e32 v246, v154
	v_exp_f32_e32 v249, v151
	v_exp_f32_e32 v248, v155
	v_exp_f32_e32 v251, v152
	v_exp_f32_e32 v250, v156
	v_exp_f32_e32 v253, v153
	v_exp_f32_e32 v252, v157
	v_cvt_pk_bf16_f32 v124, v191, v241
	v_cvt_pk_bf16_f32 v125, v243, v245
	v_cvt_pk_bf16_f32 v126, v247, v249
	v_cvt_pk_bf16_f32 v127, v251, v253
	v_cvt_pk_bf16_f32 v128, v190, v240
	v_cvt_pk_bf16_f32 v129, v242, v244
	v_cvt_pk_bf16_f32 v130, v246, v248
	v_cvt_pk_bf16_f32 v131, v250, v252
	v_add_u32_e32 v132, v132, v119
	s_waitcnt lgkmcnt(7)
	v_mfma_f32_16x16x32_bf16 v[72:75], v[174:177], v[124:127], v[72:75]
	ds_read_b128 v[150:153], v132
	ds_read_b128 v[154:157], v132 offset:2048
	v_exp_f32_e32 v201, v158
	v_exp_f32_e32 v200, v162
	v_mfma_f32_16x16x32_bf16 v[84:87], v[174:177], v[128:131], v[84:87]
	v_exp_f32_e32 v203, v159
	v_exp_f32_e32 v202, v163
	v_exp_f32_e32 v163, v160
	s_waitcnt lgkmcnt(8)
	v_mfma_f32_16x16x32_bf16 v[68:71], v[178:181], v[124:127], v[68:71]
	v_exp_f32_e32 v162, v164
	v_exp_f32_e32 v164, v170
	v_exp_f32_e32 v167, v167
	v_mfma_f32_16x16x32_bf16 v[80:83], v[178:181], v[128:131], v[80:83]
	v_exp_f32_e32 v170, v172
	v_exp_f32_e32 v169, v169
	v_cvt_pk_bf16_f32 v158, v201, v203
	s_waitcnt lgkmcnt(7)
	v_mfma_f32_16x16x32_bf16 v[60:63], v[182:185], v[124:127], v[60:63]
	v_mfma_f32_16x16x32_bf16 v[76:79], v[182:185], v[128:131], v[76:79]
	ds_read_b128 v[174:177], v132 offset:4096
	ds_read_b128 v[178:181], v132 offset:6144
	ds_read_b128 v[182:185], v132 offset:8192
	ds_read_b128 v[232:235], v132 offset:10240
	s_waitcnt lgkmcnt(10)
	v_mfma_f32_16x16x32_bf16 v[56:59], v[186:189], v[124:127], v[56:59]
	v_mfma_f32_16x16x32_bf16 v[64:67], v[186:189], v[128:131], v[64:67]
	ds_read_b128 v[186:189], v132 offset:12288
	ds_read_b128 v[236:239], v132 offset:14336
	s_waitcnt lgkmcnt(11)
	v_mfma_f32_16x16x32_bf16 v[36:39], v[216:219], v[124:127], v[36:39]
	v_mfma_f32_16x16x32_bf16 v[52:55], v[216:219], v[128:131], v[52:55]
	v_exp_f32_e32 v217, v161
	v_exp_f32_e32 v216, v165
	v_exp_f32_e32 v165, v166
	s_waitcnt lgkmcnt(10)
	v_mfma_f32_16x16x32_bf16 v[32:35], v[220:223], v[124:127], v[32:35]
	v_exp_f32_e32 v166, v171
	v_exp_f32_e32 v171, v168
	v_exp_f32_e32 v168, v173
	v_mfma_f32_16x16x32_bf16 v[48:51], v[220:223], v[128:131], v[48:51]
	v_cvt_pk_bf16_f32 v159, v163, v217
	v_cvt_pk_bf16_f32 v160, v165, v167
	v_cvt_pk_bf16_f32 v161, v171, v169
	s_waitcnt lgkmcnt(9)
	v_mfma_f32_16x16x32_bf16 v[28:31], v[224:227], v[124:127], v[28:31]
	v_mfma_f32_16x16x32_bf16 v[44:47], v[224:227], v[128:131], v[44:47]
	s_waitcnt lgkmcnt(8)
	v_mfma_f32_16x16x32_bf16 v[24:27], v[228:231], v[124:127], v[24:27]
	v_cvt_pk_bf16_f32 v124, v200, v202
	v_cvt_pk_bf16_f32 v125, v162, v216
	v_cvt_pk_bf16_f32 v126, v164, v166
	v_mfma_f32_16x16x32_bf16 v[40:43], v[228:231], v[128:131], v[40:43]
	v_cvt_pk_bf16_f32 v127, v170, v168
	s_waitcnt lgkmcnt(7)
	v_mfma_f32_16x16x32_bf16 v[84:87], v[150:153], v[124:127], v[84:87]
	v_add_f32_e64 v128, v250, v252
	v_add_f32_e64 v129, v251, v253
	s_bitcmp1_b32 s5, 0
	v_pk_add_f32 v[130:131], v[170:171], v[168:169]
	s_waitcnt lgkmcnt(6)
	v_mfma_f32_16x16x32_bf16 v[80:83], v[154:157], v[124:127], v[80:83]
	s_cselect_b32 s4, s91, 0
	v_lshl_add_u64 v[106:107], v[106:107], 0, s[66:67]
	v_lshl_add_u64 v[108:109], v[108:109], 0, s[76:77]
	s_waitcnt lgkmcnt(5)
	v_mfma_f32_16x16x32_bf16 v[76:79], v[174:177], v[124:127], v[76:79]
	s_waitcnt lgkmcnt(4)
	v_mfma_f32_16x16x32_bf16 v[64:67], v[178:181], v[124:127], v[64:67]
	s_waitcnt lgkmcnt(3)
	v_mfma_f32_16x16x32_bf16 v[52:55], v[182:185], v[124:127], v[52:55]
	s_waitcnt lgkmcnt(2)
	v_mfma_f32_16x16x32_bf16 v[48:51], v[232:235], v[124:127], v[48:51]
	s_waitcnt lgkmcnt(1)
	v_mfma_f32_16x16x32_bf16 v[44:47], v[186:189], v[124:127], v[44:47]
	s_waitcnt lgkmcnt(0)
	v_mfma_f32_16x16x32_bf16 v[40:43], v[236:239], v[124:127], v[40:43]
	v_add_f32_e64 v124, v190, v240
	v_add_f32_e64 v125, v191, v241
	v_pk_add_f32 v[126:127], v[242:243], v[244:245]
	s_nop 0
	v_pk_add_f32 v[124:125], v[124:125], v[126:127]
	v_pk_add_f32 v[126:127], v[246:247], v[248:249]
	v_mfma_f32_16x16x32_bf16 v[72:75], v[150:153], v[158:161], v[72:75]
	v_add_f32_e64 v126, v126, v128
	v_add_f32_e64 v127, v127, v129
	v_pk_add_f32 v[128:129], v[162:163], v[216:217]
	v_pk_add_f32 v[124:125], v[124:125], v[126:127]
	v_pk_add_f32 v[126:127], v[200:201], v[202:203]
	v_mfma_f32_16x16x32_bf16 v[68:71], v[154:157], v[158:161], v[68:71]
	v_add_f32_e64 v126, v126, v128
	v_add_f32_e64 v127, v127, v129
	v_pk_add_f32 v[128:129], v[164:165], v[166:167]
	v_pk_add_f32 v[110:111], v[110:111], v[124:125]
	v_mfma_f32_16x16x32_bf16 v[60:63], v[174:177], v[158:161], v[60:63]
	v_add_f32_e64 v128, v128, v130
	v_add_f32_e64 v129, v129, v131
	v_add3_u32 v124, s4, v116, v117
	s_cselect_b32 s4, s57, s70
	v_mfma_f32_16x16x32_bf16 v[56:59], v[178:181], v[158:161], v[56:59]
	v_add_f32_e64 v126, v126, v128
	v_add_f32_e64 v127, v127, v129
	s_waitcnt vmcnt(2)
	ds_write_b128 v124, v[92:95]
	ds_write_b128 v124, v[88:91] offset:16
	v_add_u32_e32 v88, s4, v122
	v_mfma_f32_16x16x32_bf16 v[36:39], v[182:185], v[158:161], v[36:39]
	v_add_f32_e64 v110, v110, v126
	v_add_f32_e64 v111, v111, v127
	s_waitcnt vmcnt(0)
	ds_write_b128 v88, v[100:103]
	v_add_u32_e32 v88, s4, v123
	v_mfma_f32_16x16x32_bf16 v[32:35], v[232:235], v[158:161], v[32:35]
	s_cmp_lg_u32 s23, s5
	s_mov_b32 s4, s5
	ds_write_b128 v88, v[96:99]
	v_mfma_f32_16x16x32_bf16 v[28:31], v[186:189], v[158:161], v[28:31]
	s_waitcnt lgkmcnt(0)
	s_barrier
	v_mfma_f32_16x16x32_bf16 v[24:27], v[236:239], v[158:161], v[24:27]
	s_cbranch_scc1 .LBB0_131
	v_add_u32_e32 v116, 0, v118
	ds_read_b128 v[88:91], v116 offset:17408
	ds_read_b128 v[92:95], v116 offset:17472
	ds_read_b128 v[96:99], v116 offset:17536
	ds_read_b128 v[100:103], v116 offset:17600
	ds_read_b128 v[106:109], v116 offset:21760
	ds_read_b128 v[122:125], v116 offset:21824
	ds_read_b128 v[126:129], v116 offset:21888
	ds_read_b128 v[150:153], v116 offset:21952
	ds_read_b128 v[154:157], v116 offset:26112
	ds_read_b128 v[158:161], v116 offset:26176
	ds_read_b128 v[162:165], v116 offset:26240
	ds_read_b128 v[166:169], v116 offset:26304
	ds_read_b128 v[170:173], v116 offset:30464
	ds_read_b128 v[174:177], v116 offset:30528
	ds_read_b128 v[178:181], v116 offset:30592
	ds_read_b128 v[182:185], v116 offset:30656
	s_waitcnt lgkmcnt(14)
	v_mfma_f32_16x16x32_bf16 v[88:91], v[88:91], v[12:15], v[16:19]
	v_mfma_f32_16x16x32_bf16 v[88:91], v[92:95], v[0:3], v[88:91]
	s_waitcnt lgkmcnt(13)
	v_mfma_f32_16x16x32_bf16 v[92:95], v[96:99], v[4:7], v[20:23]
	s_waitcnt lgkmcnt(11)
	v_mfma_f32_16x16x32_bf16 v[96:99], v[106:109], v[12:15], v[16:19]
	v_mfma_f32_16x16x32_bf16 v[92:95], v[100:103], v[8:11], v[92:95]
	s_waitcnt lgkmcnt(10)
	v_mfma_f32_16x16x32_bf16 v[96:99], v[122:125], v[0:3], v[96:99]
	s_waitcnt lgkmcnt(9)
	v_mfma_f32_16x16x32_bf16 v[100:103], v[126:129], v[4:7], v[20:23]
	s_waitcnt lgkmcnt(7)
	v_mfma_f32_16x16x32_bf16 v[106:109], v[154:157], v[12:15], v[16:19]
	s_waitcnt lgkmcnt(5)
	v_mfma_f32_16x16x32_bf16 v[122:125], v[162:165], v[4:7], v[20:23]
	s_waitcnt lgkmcnt(3)
	v_mfma_f32_16x16x32_bf16 v[12:15], v[170:173], v[12:15], v[16:19]
	s_waitcnt lgkmcnt(1)
	v_mfma_f32_16x16x32_bf16 v[4:7], v[178:181], v[4:7], v[20:23]
	v_mfma_f32_16x16x32_bf16 v[100:103], v[150:153], v[8:11], v[100:103]
	v_mfma_f32_16x16x32_bf16 v[106:109], v[158:161], v[0:3], v[106:109]
	v_mfma_f32_16x16x32_bf16 v[122:125], v[166:169], v[8:11], v[122:125]
	v_mfma_f32_16x16x32_bf16 v[0:3], v[174:177], v[0:3], v[12:15]
	s_waitcnt lgkmcnt(0)
	v_mfma_f32_16x16x32_bf16 v[4:7], v[182:185], v[8:11], v[4:7]
	v_add_u32_e32 v116, 0, v120
	v_add_u32_e32 v117, v116, v121
	v_add_u32_e32 v118, 0xc800, v117
	ds_read_b128 v[8:11], v117 offset:51200
	ds_read_b128 v[12:15], v117 offset:53248
	ds_read_b128 v[16:19], v117 offset:55296
	ds_read_b128 v[20:23], v117 offset:57344
	ds_read_b128 v[126:129], v117 offset:59392
	ds_read_b128 v[150:153], v117 offset:61440
	ds_read_b128 v[154:157], v117 offset:63488
	ds_read_b128 v[158:161], v118 offset:14336
	v_exp_f32_e32 v120, v88
	v_exp_f32_e32 v130, v92
	v_exp_f32_e32 v166, v89
	v_exp_f32_e32 v168, v93
	v_exp_f32_e32 v170, v90
	v_exp_f32_e32 v172, v94
	v_exp_f32_e32 v174, v91
	v_exp_f32_e32 v176, v95
	v_exp_f32_e32 v178, v96
	v_exp_f32_e32 v180, v100
	v_exp_f32_e32 v182, v97
	v_exp_f32_e32 v184, v101
	v_exp_f32_e32 v186, v98
	v_exp_f32_e32 v188, v102
	v_exp_f32_e32 v190, v99
	v_exp_f32_e32 v200, v103
	s_nop 0
	v_cvt_pk_bf16_f32 v88, v120, v166
	s_nop 0
	v_cvt_pk_bf16_f32 v89, v170, v174
	s_nop 0
	v_cvt_pk_bf16_f32 v90, v178, v182
	s_nop 0
	v_cvt_pk_bf16_f32 v91, v186, v190
	s_nop 0
	v_cvt_pk_bf16_f32 v92, v130, v168
	s_nop 0
	v_cvt_pk_bf16_f32 v93, v172, v176
	s_nop 0
	v_cvt_pk_bf16_f32 v94, v180, v184
	s_nop 0
	v_cvt_pk_bf16_f32 v95, v188, v200
	v_add_u32_e32 v121, v116, v119
	s_waitcnt lgkmcnt(7)
	v_mfma_f32_16x16x32_bf16 v[72:75], v[8:11], v[88:91], v[72:75]
	v_add_u32_e32 v131, 0xc800, v121
	v_exp_f32_e32 v167, v107
	v_exp_f32_e32 v169, v123
	v_mfma_f32_16x16x32_bf16 v[8:11], v[8:11], v[92:95], v[84:87]
	v_exp_f32_e32 v171, v108
	v_exp_f32_e32 v173, v124
	v_exp_f32_e32 v175, v109
	s_waitcnt lgkmcnt(6)
	v_mfma_f32_16x16x32_bf16 v[68:71], v[12:15], v[88:91], v[68:71]
	v_exp_f32_e32 v177, v125
	v_exp_f32_e32 v179, v0
	v_exp_f32_e32 v181, v4
	v_mfma_f32_16x16x32_bf16 v[12:15], v[12:15], v[92:95], v[80:83]
	v_exp_f32_e32 v183, v1
	v_exp_f32_e32 v185, v5
	v_exp_f32_e32 v187, v2
	s_waitcnt lgkmcnt(5)
	v_mfma_f32_16x16x32_bf16 v[60:63], v[16:19], v[88:91], v[60:63]
	v_exp_f32_e32 v189, v6
	v_exp_f32_e32 v191, v3
	v_exp_f32_e32 v201, v7
	v_mfma_f32_16x16x32_bf16 v[16:19], v[16:19], v[92:95], v[76:79]
	s_nop 2
	ds_read_b128 v[76:79], v121 offset:51200
	ds_read_b128 v[80:83], v121 offset:53248
	ds_read_b128 v[84:87], v121 offset:55296
	ds_read_b128 v[96:99], v121 offset:57344
	ds_read_b128 v[100:103], v121 offset:59392
	ds_read_b128 v[116:119], v121 offset:61440
	s_nop 0
	v_cvt_pk_bf16_f32 v1, v171, v175
	s_waitcnt lgkmcnt(10)
	v_mfma_f32_16x16x32_bf16 v[56:59], v[20:23], v[88:91], v[56:59]
	s_nop 0
	v_cvt_pk_bf16_f32 v2, v179, v183
	s_nop 0
	v_cvt_pk_bf16_f32 v3, v187, v191
	v_mfma_f32_16x16x32_bf16 v[20:23], v[20:23], v[92:95], v[64:67]
	s_nop 2
	ds_read_b128 v[64:67], v121 offset:63488
	ds_read_b128 v[162:165], v131 offset:14336
	v_exp_f32_e32 v121, v106
	v_exp_f32_e32 v131, v122
	s_waitcnt lgkmcnt(11)
	v_mfma_f32_16x16x32_bf16 v[36:39], v[126:129], v[88:91], v[36:39]
	s_nop 0
	v_cvt_pk_bf16_f32 v0, v121, v167
	v_mfma_f32_16x16x32_bf16 v[52:55], v[126:129], v[92:95], v[52:55]
	s_waitcnt lgkmcnt(10)
	v_mfma_f32_16x16x32_bf16 v[32:35], v[150:153], v[88:91], v[32:35]
	v_mfma_f32_16x16x32_bf16 v[48:51], v[150:153], v[92:95], v[48:51]
	s_waitcnt lgkmcnt(9)
	v_mfma_f32_16x16x32_bf16 v[28:31], v[154:157], v[88:91], v[28:31]
	v_mfma_f32_16x16x32_bf16 v[4:7], v[154:157], v[92:95], v[44:47]
	s_nop 0
	v_cvt_pk_bf16_f32 v44, v131, v169
	s_nop 0
	v_cvt_pk_bf16_f32 v45, v173, v177
	s_nop 0
	v_cvt_pk_bf16_f32 v46, v181, v185
	s_waitcnt lgkmcnt(8)
	v_mfma_f32_16x16x32_bf16 v[24:27], v[158:161], v[88:91], v[24:27]
	s_nop 0
	v_cvt_pk_bf16_f32 v47, v189, v201
	v_mfma_f32_16x16x32_bf16 v[40:43], v[158:161], v[92:95], v[40:43]
	s_waitcnt lgkmcnt(7)
	v_mfma_f32_16x16x32_bf16 v[72:75], v[76:79], v[0:3], v[72:75]
	s_waitcnt lgkmcnt(0)
	s_barrier
	v_mfma_f32_16x16x32_bf16 v[8:11], v[76:79], v[44:47], v[8:11]
	v_add_f32_e64 v76, v130, v168
	v_add_f32_e64 v77, v131, v169
	v_pk_add_f32 v[78:79], v[172:173], v[176:177]
	v_mfma_f32_16x16x32_bf16 v[68:71], v[80:83], v[0:3], v[68:71]
	v_add_f32_e64 v76, v76, v78
	v_add_f32_e64 v77, v77, v79
	v_pk_add_f32 v[78:79], v[180:181], v[184:185]
	v_mfma_f32_16x16x32_bf16 v[12:15], v[80:83], v[44:47], v[12:15]
	v_add_f32_e64 v80, v188, v200
	v_add_f32_e64 v81, v189, v201
	v_pk_add_f32 v[78:79], v[78:79], v[80:81]
	v_pk_add_f32 v[80:81], v[186:187], v[190:191]
	v_pk_add_f32 v[76:77], v[76:77], v[78:79]
	v_pk_add_f32 v[78:79], v[170:171], v[174:175]
	v_add_f32_e32 v76, v110, v76
	v_add_f32_e32 v82, v76, v77
	v_pk_add_f32 v[76:77], v[120:121], v[166:167]
	v_mfma_f32_16x16x32_bf16 v[28:31], v[64:67], v[0:3], v[28:31]
	v_add_f32_e64 v76, v76, v78
	v_add_f32_e64 v77, v77, v79
	v_pk_add_f32 v[78:79], v[178:179], v[182:183]
	v_mfma_f32_16x16x32_bf16 v[64:67], v[64:67], v[44:47], v[4:7]
	s_nop 2
	v_add_f32_e64 v4, v78, v80
	v_add_f32_e64 v5, v79, v81
	v_mfma_f32_16x16x32_bf16 v[60:63], v[84:87], v[0:3], v[60:63]
	v_add_f32_e64 v4, v76, v4
	v_add_f32_e64 v5, v77, v5
	v_add_f32_e32 v4, v111, v4
	v_mfma_f32_16x16x32_bf16 v[16:19], v[84:87], v[44:47], v[16:19]
	v_mfma_f32_16x16x32_bf16 v[56:59], v[96:99], v[0:3], v[56:59]
	v_mfma_f32_16x16x32_bf16 v[20:23], v[96:99], v[44:47], v[20:23]
	v_mfma_f32_16x16x32_bf16 v[36:39], v[100:103], v[0:3], v[36:39]
	v_mfma_f32_16x16x32_bf16 v[52:55], v[100:103], v[44:47], v[52:55]
	v_mfma_f32_16x16x32_bf16 v[32:35], v[116:119], v[0:3], v[32:35]
	v_mfma_f32_16x16x32_bf16 v[48:51], v[116:119], v[44:47], v[48:51]
	v_mfma_f32_16x16x32_bf16 v[24:27], v[162:165], v[0:3], v[24:27]
	v_add_f32_e32 v0, v4, v5
	v_mfma_f32_16x16x32_bf16 v[40:43], v[162:165], v[44:47], v[40:43]
	s_setprio 0
	ds_bpermute_b32 v1, v114, v0
	ds_bpermute_b32 v2, v114, v82
	s_waitcnt lgkmcnt(1)
	v_add_f32_e32 v0, v0, v1
	s_waitcnt lgkmcnt(0)
	v_add_f32_e32 v1, v82, v2
	ds_bpermute_b32 v2, v115, v0
	ds_bpermute_b32 v3, v115, v1
	s_waitcnt lgkmcnt(1)
	v_add_f32_e32 v0, v0, v2
	v_div_scale_f32 v2, s[4:5], v0, v0, 1.0
	v_rcp_f32_e32 v4, v2
	s_waitcnt lgkmcnt(0)
	v_add_f32_e32 v1, v1, v3
	v_div_scale_f32 v3, vcc, 1.0, v0, 1.0
	v_fma_f32 v7, -v2, v4, 1.0
	v_fmac_f32_e32 v4, v7, v4
	v_div_scale_f32 v5, s[4:5], v1, v1, v113
	v_mul_f32_e32 v7, v3, v4
	v_rcp_f32_e32 v6, v5
	v_fma_f32 v44, -v2, v7, v3
	v_fmac_f32_e32 v7, v44, v4
	v_fma_f32 v2, -v2, v7, v3
	v_div_fmas_f32 v2, v2, v4, v7
	v_div_fixup_f32 v44, v2, v0, 1.0
	v_fma_f32 v0, -v5, v6, 1.0
	v_fmac_f32_e32 v6, v0, v6
	v_div_scale_f32 v0, vcc, v113, v1, v113
	v_mul_f32_e32 v2, v0, v6
	v_fma_f32 v3, -v5, v2, v0
	v_fmac_f32_e32 v2, v3, v6
	v_fma_f32 v0, -v5, v2, v0
	v_div_fmas_f32 v0, v0, v6, v2
	s_mov_b64 s[4:5], s[0:1]
	v_div_fixup_f32 v46, v0, v1, v113
	v_pk_mul_f32 v[0:1], v[8:9], v[46:47] op_sel_hi:[1,0]
	v_pk_mul_f32 v[2:3], v[10:11], v[46:47] op_sel_hi:[1,0]
	s_load_dwordx2 s[4:5], s[4:5], 0x78
	v_pk_fma_f32 v[74:75], v[74:75], v[44:45], v[2:3] op_sel_hi:[1,0,1] neg_lo:[0,0,1] neg_hi:[0,0,1]
	v_pk_fma_f32 v[72:73], v[72:73], v[44:45], v[0:1] op_sel_hi:[1,0,1] neg_lo:[0,0,1] neg_hi:[0,0,1]
	v_pk_mul_f32 v[0:1], v[12:13], v[46:47] op_sel_hi:[1,0]
	v_pk_mul_f32 v[2:3], v[14:15], v[46:47] op_sel_hi:[1,0]
	v_pk_fma_f32 v[68:69], v[68:69], v[44:45], v[0:1] op_sel_hi:[1,0,1] neg_lo:[0,0,1] neg_hi:[0,0,1]
	v_pk_fma_f32 v[70:71], v[70:71], v[44:45], v[2:3] op_sel_hi:[1,0,1] neg_lo:[0,0,1] neg_hi:[0,0,1]
	v_pk_mul_f32 v[0:1], v[16:17], v[46:47] op_sel_hi:[1,0]
	v_pk_mul_f32 v[2:3], v[18:19], v[46:47] op_sel_hi:[1,0]
	v_pk_fma_f32 v[60:61], v[60:61], v[44:45], v[0:1] op_sel_hi:[1,0,1] neg_lo:[0,0,1] neg_hi:[0,0,1]
	v_pk_fma_f32 v[16:17], v[62:63], v[44:45], v[2:3] op_sel_hi:[1,0,1] neg_lo:[0,0,1] neg_hi:[0,0,1]
	v_pk_mul_f32 v[0:1], v[20:21], v[46:47] op_sel_hi:[1,0]
	v_pk_mul_f32 v[2:3], v[22:23], v[46:47] op_sel_hi:[1,0]
	v_pk_fma_f32 v[14:15], v[56:57], v[44:45], v[0:1] op_sel_hi:[1,0,1] neg_lo:[0,0,1] neg_hi:[0,0,1]
	v_pk_fma_f32 v[12:13], v[58:59], v[44:45], v[2:3] op_sel_hi:[1,0,1] neg_lo:[0,0,1] neg_hi:[0,0,1]
	v_pk_mul_f32 v[0:1], v[52:53], v[46:47] op_sel_hi:[1,0]
	v_pk_mul_f32 v[2:3], v[54:55], v[46:47] op_sel_hi:[1,0]
	v_pk_fma_f32 v[10:11], v[36:37], v[44:45], v[0:1] op_sel_hi:[1,0,1] neg_lo:[0,0,1] neg_hi:[0,0,1]
	v_pk_fma_f32 v[8:9], v[38:39], v[44:45], v[2:3] op_sel_hi:[1,0,1] neg_lo:[0,0,1] neg_hi:[0,0,1]
	v_pk_mul_f32 v[0:1], v[48:49], v[46:47] op_sel_hi:[1,0]
	v_pk_mul_f32 v[2:3], v[50:51], v[46:47] op_sel_hi:[1,0]
	s_waitcnt lgkmcnt(0)
	s_add_u32 s4, s4, s8
	v_pk_fma_f32 v[4:5], v[34:35], v[44:45], v[2:3] op_sel_hi:[1,0,1] neg_lo:[0,0,1] neg_hi:[0,0,1]
	v_pk_fma_f32 v[6:7], v[32:33], v[44:45], v[0:1] op_sel_hi:[1,0,1] neg_lo:[0,0,1] neg_hi:[0,0,1]
	v_pk_mul_f32 v[2:3], v[64:65], v[46:47] op_sel_hi:[1,0]
	v_pk_mul_f32 v[0:1], v[66:67], v[46:47] op_sel_hi:[1,0]
	v_pk_mul_f32 v[18:19], v[40:41], v[46:47] op_sel_hi:[1,0]
	v_pk_mul_f32 v[20:21], v[42:43], v[46:47] op_sel_hi:[1,0]
	s_addc_u32 s5, s5, s9
	v_lshlrev_b32_e32 v46, 4, v105
	v_pk_fma_f32 v[0:1], v[30:31], v[44:45], v[0:1] op_sel_hi:[1,0,1] neg_lo:[0,0,1] neg_hi:[0,0,1]
	v_pk_fma_f32 v[2:3], v[28:29], v[44:45], v[2:3] op_sel_hi:[1,0,1] neg_lo:[0,0,1] neg_hi:[0,0,1]
	v_pk_fma_f32 v[50:51], v[26:27], v[44:45], v[20:21] op_sel_hi:[1,0,1] neg_lo:[0,0,1] neg_hi:[0,0,1]
	v_pk_fma_f32 v[52:53], v[24:25], v[44:45], v[18:19] op_sel_hi:[1,0,1] neg_lo:[0,0,1] neg_hi:[0,0,1]
	global_load_dwordx4 v[18:21], v46, s[4:5]
	global_load_dwordx4 v[22:25], v46, s[4:5] offset:64
	global_load_dwordx4 v[26:29], v46, s[4:5] offset:128
	global_load_dwordx4 v[30:33], v46, s[4:5] offset:192
	global_load_dwordx4 v[34:37], v46, s[4:5] offset:256
	global_load_dwordx4 v[38:41], v46, s[4:5] offset:320
	global_load_dwordx4 v[42:45], v46, s[4:5] offset:384
	s_nop 0
	global_load_dwordx4 v[46:49], v46, s[4:5] offset:448
	v_mov_b32_e32 v56, v73
	v_mov_b32_e32 v57, v69
	v_mov_b32_e32 v54, v72
	v_mov_b32_e32 v55, v68
	v_pk_mul_f32 v[56:57], v[56:57], v[56:57]
	v_mov_b32_e32 v58, v15
	v_pk_fma_f32 v[54:55], v[54:55], v[54:55], v[56:57]
	v_mov_b32_e32 v56, v74
	v_mov_b32_e32 v57, v70
	v_pk_fma_f32 v[54:55], v[56:57], v[56:57], v[54:55]
	v_mov_b32_e32 v56, v75
	v_mov_b32_e32 v57, v71
	v_mov_b32_e32 v59, v61
	v_pk_fma_f32 v[54:55], v[56:57], v[56:57], v[54:55]
	v_mov_b32_e32 v56, v14
	v_mov_b32_e32 v57, v60
	v_pk_mul_f32 v[58:59], v[58:59], v[58:59]
	v_mov_b32_e32 v62, v7
	v_pk_fma_f32 v[56:57], v[56:57], v[56:57], v[58:59]
	v_mov_b32_e32 v58, v12
	v_mov_b32_e32 v59, v16
	v_pk_fma_f32 v[56:57], v[58:59], v[58:59], v[56:57]
	v_mov_b32_e32 v58, v13
	v_mov_b32_e32 v59, v17
	v_mov_b32_e32 v63, v11
	v_pk_fma_f32 v[56:57], v[58:59], v[58:59], v[56:57]
	v_mov_b32_e32 v58, v6
	v_mov_b32_e32 v59, v10
	v_pk_mul_f32 v[62:63], v[62:63], v[62:63]
	v_mov_b32_e32 v64, v53
	v_pk_fma_f32 v[58:59], v[58:59], v[58:59], v[62:63]
	v_mov_b32_e32 v62, v4
	v_mov_b32_e32 v63, v8
	v_pk_fma_f32 v[58:59], v[62:63], v[62:63], v[58:59]
	v_mov_b32_e32 v62, v5
	v_mov_b32_e32 v63, v9
	v_mov_b32_e32 v65, v3
	v_add_f32_e32 v54, v54, v55
	v_pk_fma_f32 v[58:59], v[62:63], v[62:63], v[58:59]
	v_mov_b32_e32 v62, v52
	v_mov_b32_e32 v63, v2
	v_pk_mul_f32 v[64:65], v[64:65], v[64:65]
	v_add_f32_e32 v54, v57, v54
	v_pk_fma_f32 v[62:63], v[62:63], v[62:63], v[64:65]
	v_mov_b32_e32 v64, v50
	v_mov_b32_e32 v65, v0
	v_add_f32_e32 v54, v56, v54
	v_pk_fma_f32 v[62:63], v[64:65], v[64:65], v[62:63]
	v_mov_b32_e32 v64, v51
	v_mov_b32_e32 v65, v1
	v_add_f32_e32 v54, v59, v54
	v_pk_fma_f32 v[62:63], v[64:65], v[64:65], v[62:63]
	v_add_f32_e32 v54, v58, v54
	v_add_f32_e32 v54, v63, v54
	v_add_f32_e32 v54, v62, v54
	ds_bpermute_b32 v55, v114, v54
	v_sub_f32_e32 v56, 1.0, v112
	s_waitcnt lgkmcnt(0)
	v_add_f32_e32 v54, v54, v55
	ds_bpermute_b32 v55, v115, v54
	s_waitcnt lgkmcnt(0)
	v_add_f32_e32 v54, v54, v55
	v_fmamk_f32 v54, v54, 0x3c000000, v137
	v_mul_f32_e32 v55, 0x4b800000, v54
	v_cmp_gt_f32_e32 vcc, s94, v54
	s_nop 1
	v_cndmask_b32_e32 v54, v54, v55, vcc
	v_rsq_f32_e32 v54, v54
	s_nop 0
	v_mul_f32_e32 v55, 0x45800000, v54
	v_cndmask_b32_e32 v54, v54, v55, vcc
	v_mul_f32_e32 v54, v56, v54
	v_mov_b64_e32 v[56:57], s[12:13]
	v_mad_i64_i32 v[56:57], s[4:5], v104, s96, v[56:57]
	s_lshl_b32 s58, s22, 1
	v_pk_mul_f32 v[58:59], v[72:73], v[54:55] op_sel_hi:[1,0]
	v_lshl_add_u64 v[56:57], v[56:57], 0, s[58:59]
	v_lshlrev_b32_e32 v132, 3, v105
	v_pk_mul_f32 v[62:63], v[74:75], v[54:55] op_sel_hi:[1,0]
	s_waitcnt vmcnt(7)
	v_pk_mul_f32 v[18:19], v[18:19], v[58:59]
	v_lshl_add_u64 v[56:57], v[56:57], 0, v[132:133]
	v_pk_mul_f32 v[20:21], v[20:21], v[62:63]
	v_cvt_pk_bf16_f32 v18, v18, v19
	v_pk_mul_f32 v[2:3], v[2:3], v[54:55] op_sel_hi:[1,0]
	v_cvt_pk_bf16_f32 v19, v20, v21
	global_store_dwordx2 v[56:57], v[18:19], off
	v_pk_mul_f32 v[18:19], v[68:69], v[54:55] op_sel_hi:[1,0]
	v_pk_mul_f32 v[20:21], v[70:71], v[54:55] op_sel_hi:[1,0]
	s_waitcnt vmcnt(7)
	v_pk_mul_f32 v[18:19], v[22:23], v[18:19]
	v_pk_mul_f32 v[0:1], v[0:1], v[54:55] op_sel_hi:[1,0]
	v_pk_mul_f32 v[20:21], v[24:25], v[20:21]
	v_cvt_pk_bf16_f32 v18, v18, v19
	s_waitcnt vmcnt(2)
	v_pk_mul_f32 v[0:1], v[44:45], v[0:1]
	v_cvt_pk_bf16_f32 v19, v20, v21
	v_pk_mul_f32 v[2:3], v[42:43], v[2:3]
	global_store_dwordx2 v[56:57], v[18:19], off offset:32
	v_pk_mul_f32 v[18:19], v[60:61], v[54:55] op_sel_hi:[1,0]
	v_pk_mul_f32 v[14:15], v[14:15], v[54:55] op_sel_hi:[1,0]
	v_pk_mul_f32 v[10:11], v[10:11], v[54:55] op_sel_hi:[1,0]
	v_pk_mul_f32 v[6:7], v[6:7], v[54:55] op_sel_hi:[1,0]
	v_cvt_pk_bf16_f32 v2, v2, v3
	v_cvt_pk_bf16_f32 v3, v0, v1
	v_pk_mul_f32 v[0:1], v[52:53], v[54:55] op_sel_hi:[1,0]
	v_pk_mul_f32 v[16:17], v[16:17], v[54:55] op_sel_hi:[1,0]
	v_pk_mul_f32 v[18:19], v[26:27], v[18:19]
	v_pk_mul_f32 v[12:13], v[12:13], v[54:55] op_sel_hi:[1,0]
	v_pk_mul_f32 v[14:15], v[30:31], v[14:15]
	v_pk_mul_f32 v[8:9], v[8:9], v[54:55] op_sel_hi:[1,0]
	v_pk_mul_f32 v[10:11], v[34:35], v[10:11]
	v_pk_mul_f32 v[4:5], v[4:5], v[54:55] op_sel_hi:[1,0]
	v_pk_mul_f32 v[6:7], v[38:39], v[6:7]
	global_store_dwordx2 v[56:57], v[2:3], off offset:192
	v_pk_mul_f32 v[2:3], v[50:51], v[54:55] op_sel_hi:[1,0]
	s_waitcnt vmcnt(3)
	v_pk_mul_f32 v[0:1], v[46:47], v[0:1]
	s_mov_b64 s[4:5], 0
	v_pk_mul_f32 v[16:17], v[28:29], v[16:17]
	v_cvt_pk_bf16_f32 v18, v18, v19
	v_pk_mul_f32 v[12:13], v[32:33], v[12:13]
	v_cvt_pk_bf16_f32 v19, v16, v17
	global_store_dwordx2 v[56:57], v[18:19], off offset:64
	v_cvt_pk_bf16_f32 v14, v14, v15
	v_cvt_pk_bf16_f32 v15, v12, v13
	global_store_dwordx2 v[56:57], v[14:15], off offset:96
	v_pk_mul_f32 v[8:9], v[36:37], v[8:9]
	v_cvt_pk_bf16_f32 v10, v10, v11
	v_pk_mul_f32 v[4:5], v[40:41], v[4:5]
	v_cvt_pk_bf16_f32 v11, v8, v9
	global_store_dwordx2 v[56:57], v[10:11], off offset:128
	v_cvt_pk_bf16_f32 v6, v6, v7
	v_cvt_pk_bf16_f32 v7, v4, v5
	global_store_dwordx2 v[56:57], v[6:7], off offset:160
	v_pk_mul_f32 v[2:3], v[48:49], v[2:3]
	v_cvt_pk_bf16_f32 v0, v0, v1
	s_nop 0
	v_cvt_pk_bf16_f32 v1, v2, v3
	global_store_dwordx2 v[56:57], v[0:1], off offset:224
	s_branch .LBB0_77
